# RMS+forget phase: log_sigmoid deferred and run once per 8 rows on all 64 lanes (one row per 8-lane slot) instead of per row on 8 lanes; partial batch flushed at loop end
# speedup vs baseline: 1.0161x; 1.0016x over previous
.LBB0_638:
	s_or_b64 exec, exec, s[24:25]
	v_ashrrev_i32_e32 v0, 6, v2
	v_readlane_b32 s4, v254, 18
	s_waitcnt vmcnt(0) lgkmcnt(0)
	s_barrier
	v_add_u32_e32 v142, s4, v0
	s_mov_b32 s4, 0x8100
	v_cmp_gt_i32_e32 vcc, s4, v142
	s_mov_b32 s96, 0
	s_mov_b32 s97, 0
	s_and_saveexec_b64 s[24:25], vcc
	s_cbranch_execz .LBB0_649
	v_and_b32_e32 v0, 64, v218
	v_add_u32_e32 v0, 64, v0
	v_xor_b32_e32 v3, 1, v218
	v_cmp_lt_i32_e32 vcc, v3, v0
	s_add_u32 s48, s44, 0x8000000
	s_addc_u32 s49, s45, 0
	v_cndmask_b32_e32 v3, v218, v3, vcc
	v_lshlrev_b32_e32 v160, 2, v3
	v_xor_b32_e32 v3, 2, v218
	v_cmp_lt_i32_e32 vcc, v3, v0
	s_lshl_b32 s28, s64, 3
	s_lshl_b64 s[4:5], s[28:29], 2
	v_cndmask_b32_e32 v3, v218, v3, vcc
	v_lshlrev_b32_e32 v161, 2, v3
	v_xor_b32_e32 v3, 4, v218
	v_cmp_lt_i32_e32 vcc, v3, v0
	s_add_u32 s8, s38, s4
	v_and_b32_e32 v130, 63, v2
	v_cndmask_b32_e32 v3, v218, v3, vcc
	v_lshlrev_b32_e32 v162, 2, v3
	v_xor_b32_e32 v3, 8, v218
	v_cmp_lt_i32_e32 vcc, v3, v0
	s_addc_u32 s9, s39, s5
	v_lshl_add_u32 v126, v130, 4, 0
	v_cndmask_b32_e32 v3, v218, v3, vcc
	v_lshlrev_b32_e32 v163, 2, v3
	v_xor_b32_e32 v3, 16, v218
	v_cmp_lt_i32_e32 vcc, v3, v0
	s_lshl_b64 s[4:5], s[64:65], 20
	s_add_u32 s4, s44, s4
	v_cndmask_b32_e32 v3, v218, v3, vcc
	v_lshlrev_b32_e32 v164, 2, v3
	v_xor_b32_e32 v3, 32, v218
	v_cmp_lt_i32_e32 vcc, v3, v0
	s_addc_u32 s5, s45, s5
	s_add_u32 s4, s4, 0x1831c000
	v_cndmask_b32_e32 v0, v218, v3, vcc
	v_lshlrev_b32_e32 v165, 2, v0
	v_and_b32_e32 v0, 1, v2
	v_and_b32_e32 v3, 2, v2
	v_cmp_eq_u32_e32 vcc, 0, v0
	v_lshlrev_b32_e32 v0, 2, v130
	v_cmp_eq_u32_e64 s[38:39], 0, v3
	v_and_b32_e32 v3, 4, v2
	v_xor_b32_e32 v166, 4, v0
	v_xor_b32_e32 v167, 8, v0
	v_cmp_eq_u32_e64 s[40:41], 0, v3
	v_xor_b32_e32 v168, 16, v0
	v_xor_b32_e32 v169, 32, v0
	v_xor_b32_e32 v170, 64, v0
	v_xor_b32_e32 v171, 0x80, v0
	v_bfrev_b32_e32 v0, v2
	ds_read_b128 v[2:5], v126
	ds_read_b128 v[6:9], v126 offset:1024
	ds_read_b128 v[10:13], v126 offset:2048
	ds_read_b128 v[14:17], v126 offset:3072
	ds_read_b128 v[18:21], v126 offset:4096
	ds_read_b128 v[22:25], v126 offset:5120
	ds_read_b128 v[26:29], v126 offset:6144
	ds_read_b128 v[30:33], v126 offset:7168
	ds_read_b128 v[34:37], v126 offset:8192
	ds_read_b128 v[38:41], v126 offset:9216
	ds_read_b128 v[42:45], v126 offset:10240
	ds_read_b128 v[46:49], v126 offset:11264
	ds_read_b128 v[50:53], v126 offset:12288
	ds_read_b128 v[54:57], v126 offset:13312
	ds_read_b128 v[58:61], v126 offset:14336
	ds_read_b128 v[62:65], v126 offset:15360
	ds_read_b128 v[66:69], v126 offset:16384
	ds_read_b128 v[70:73], v126 offset:17408
	ds_read_b128 v[74:77], v126 offset:18432
	ds_read_b128 v[78:81], v126 offset:19456
	ds_read_b128 v[82:85], v126 offset:20480
	ds_read_b128 v[86:89], v126 offset:21504
	ds_read_b128 v[90:93], v126 offset:22528
	ds_read_b128 v[94:97], v126 offset:23552
	ds_read_b128 v[98:101], v126 offset:24576
	ds_read_b128 v[102:105], v126 offset:25600
	ds_read_b128 v[106:109], v126 offset:26624
	ds_read_b128 v[110:113], v126 offset:27648
	ds_read_b128 v[114:117], v126 offset:28672
	ds_read_b128 v[118:121], v126 offset:29696
	ds_read_b128 v[122:125], v126 offset:30720
	ds_read_b128 v[126:129], v126 offset:31744
	s_addc_u32 s5, s5, 0
	s_lshl_b64 s[10:11], s[64:65], 13
	s_add_u32 s10, s44, s10
	v_lshrrev_b32_e32 v132, 29, v0
	s_addc_u32 s11, s45, s11
	v_lshlrev_b32_e32 v0, 2, v132
	v_ashrrev_i32_e32 v143, 31, v142
	s_add_u32 s28, s10, 0x1871c000
	v_lshl_add_u64 v[144:145], s[8:9], 0, v[0:1]
	global_load_dword v241, v[144:145], off
	v_lshlrev_b32_e32 v0, 3, v130
	v_lshlrev_b64 v[134:135], 12, v[142:143]
	s_addc_u32 s52, s11, 0
	v_cmp_gt_u32_e64 s[42:43], 8, v130
	v_lshl_add_u64 v[146:147], s[78:79], 0, v[0:1]
	v_lshl_add_u64 v[148:149], s[44:45], 0, v[134:135]
	s_mov_b64 s[50:51], 0
	v_lshlrev_b32_e32 v0, 4, v130
	v_lshlrev_b32_e32 v150, 2, v132
	s_mov_b64 s[100:101], s[44:45]
	v_lshl_or_b32 v240, v142, 12, v0
	global_load_dwordx4 v[224:227], v240, s[100:101]
	global_load_dwordx4 v[228:231], v240, s[100:101] offset:1024
	global_load_dwordx4 v[232:235], v240, s[100:101] offset:2048
	global_load_dwordx4 v[236:239], v240, s[100:101] offset:3072
	s_waitcnt vmcnt(0)
	v_lshrrev_b32_e32 v244, 3, v130
	v_mov_b32_e32 v243, -1
	v_mov_b32_e32 v242, 0
	s_branch .LBB0_642
.LBB0_640:
	s_or_b64 exec, exec, s[54:55]
	s_mov_b32 s8, 0x8000
	v_cmp_gt_i32_e64 s[46:47], s8, v243
	v_add_u32_e32 v132, 0xffff8000, v243
	v_cndmask_b32_e64 v132, v132, v243, s[46:47]
	v_lshlrev_b32_e32 v132, 5, v132
	v_mov_b32_e32 v133, v1
	v_mov_b32_e32 v134, s28
	v_mov_b32_e32 v135, s52
	v_mov_b32_e32 v136, s4
	v_mov_b32_e32 v137, s5
	v_cndmask_b32_e64 v134, v134, v136, s[46:47]
	v_cndmask_b32_e64 v135, v135, v137, s[46:47]
	v_lshl_add_u64 v[132:133], v[134:135], 0, v[132:133]
	v_mov_b32_e32 v151, v1
	v_lshl_add_u64 v[132:133], v[132:133], 0, v[150:151]
	global_store_dword v[132:133], v131, off
.Lrmsf_fl_end:
	s_or_b64 exec, exec, s[56:57]
	v_mov_b32_e32 v243, -1
	s_cmp_lg_u32 s97, 0
	s_cbranch_scc1 .Lrmsf_done
.LBB0_641:
	v_readlane_b32 s8, v254, 55
	v_readlane_b32 s9, v254, 56
	s_nop 1
	v_lshl_add_u64 v[142:143], v[142:143], 0, s[8:9]
	s_mov_b32 s8, 0x80ff
	v_cmp_lt_i32_e64 s[44:45], s8, v142
	v_readlane_b32 s8, v254, 62
	v_readlane_b32 s9, v254, 63
	s_or_b64 s[50:51], s[44:45], s[50:51]
	s_nop 0
	v_lshl_add_u64 v[148:149], v[148:149], 0, s[8:9]
	s_andn2_b64 exec, exec, s[50:51]
	s_cbranch_execz .LBB0_649
.LBB0_642:
	s_waitcnt vmcnt(4)
	s_mov_b32 s8, 0x8000
	v_cmp_gt_i32_e64 s[44:45], s8, v142
	v_cmp_lt_i32_e64 s[46:47], s91, v142
	v_add_u32_e32 v152, 0xffff8000, v142
	v_mov_b64_e32 v[154:155], v[142:143]
	s_waitcnt lgkmcnt(0)
	v_mov_b64_e32 v[130:131], v[148:149]
	s_and_saveexec_b64 s[54:55], s[46:47]
	v_mov_b32_e32 v153, v1
	v_lshlrev_b64 v[130:131], 12, v[152:153]
	v_lshl_add_u64 v[130:131], s[48:49], 0, v[130:131]
	v_mov_b32_e32 v154, v142
	v_mov_b32_e32 v155, v1
	s_or_b64 exec, exec, s[54:55]
	v_lshl_add_u64 v[130:131], v[130:131], 0, v[0:1]
	v_mov_b64_e32 v[172:173], v[224:225]
	v_mov_b64_e32 v[174:175], v[226:227]
	v_mov_b64_e32 v[138:139], v[228:229]
	v_mov_b64_e32 v[140:141], v[230:231]
	s_mov_b32 s8, 0x800000
	v_pk_mul_f32 v[132:133], v[174:175], v[174:175]
	v_pk_mul_f32 v[134:135], v[172:173], v[172:173]
	s_nop 0
	v_pk_mov_b32 v[136:137], v[134:135], v[132:133] op_sel:[1,0]
	v_mov_b32_e32 v135, v133
	v_pk_add_f32 v[156:157], v[136:137], v[134:135]
	v_pk_mul_f32 v[132:133], v[140:141], v[140:141]
	v_pk_mul_f32 v[134:135], v[138:139], v[138:139]
	v_pk_add_f32 v[156:157], v[156:157], v[156:157] op_sel:[0,1] op_sel_hi:[1,0]
	v_pk_mov_b32 v[136:137], v[134:135], v[132:133] op_sel:[1,0]
	v_mov_b32_e32 v135, v133
	v_pk_add_f32 v[158:159], v[136:137], v[134:135]
	v_mov_b64_e32 v[134:135], v[232:233]
	v_mov_b64_e32 v[136:137], v[234:235]
	s_nop 0
	v_mov_b64_e32 v[130:131], v[236:237]
	v_mov_b64_e32 v[132:133], v[238:239]
	v_readlane_b32 s10, v254, 55
	s_mov_b32 s11, 0x80ff
	v_add_u32_e32 v240, s10, v142
	v_min_i32_e32 v240, s11, v240
	v_lshl_or_b32 v240, v240, 12, v0
	global_load_dwordx4 v[224:227], v240, s[100:101]
	global_load_dwordx4 v[228:231], v240, s[100:101] offset:1024
	global_load_dwordx4 v[232:235], v240, s[100:101] offset:2048
	global_load_dwordx4 v[236:239], v240, s[100:101] offset:3072
	v_pk_add_f32 v[158:159], v[158:159], v[158:159] op_sel:[0,1] op_sel_hi:[1,0]
	v_mul_f32_e32 v151, v130, v130
	v_mul_f32_e32 v153, v131, v131
	v_mov_b32_e32 v157, v151
	v_mov_b32_e32 v159, v153
	v_pk_add_f32 v[156:157], v[156:157], v[158:159]
	v_mul_f32_e32 v158, v135, v135
	v_mul_f32_e32 v176, v132, v132
	v_pk_fma_f32 v[158:159], v[134:135], v[134:135], v[158:159] op_sel_hi:[1,1,0]
	v_mul_f32_e32 v178, v133, v133
	v_mov_b32_e32 v159, v176
	v_mul_f32_e32 v176, v137, v137
	v_pk_fma_f32 v[176:177], v[136:137], v[136:137], v[176:177] op_sel_hi:[1,1,0]
	s_nop 0
	v_mov_b32_e32 v177, v178
	v_pk_add_f32 v[158:159], v[158:159], v[176:177]
	v_lshlrev_b64 v[178:179], 11, v[154:155]
	v_pk_add_f32 v[156:157], v[156:157], v[158:159]
	s_nop 0
	v_add_f32_e32 v151, v156, v157
	s_nop 1
	v_add_f32_dpp v151, v151, v151 quad_perm:[1,0,3,2] row_mask:0xf bank_mask:0xf
	s_nop 1
	v_add_f32_dpp v151, v151, v151 quad_perm:[2,3,0,1] row_mask:0xf bank_mask:0xf
	s_nop 1
	v_add_f32_dpp v151, v151, v151 row_half_mirror row_mask:0xf bank_mask:0xf
	s_nop 1
	v_add_f32_dpp v151, v151, v151 row_mirror row_mask:0xf bank_mask:0xf
	s_nop 1
	v_add_f32_dpp v151, v151, v151 row_bcast:15 row_mask:0xa bank_mask:0xf
	s_nop 1
	v_add_f32_dpp v151, v151, v151 row_bcast:31 row_mask:0xc bank_mask:0xf
	s_nop 1
	v_readlane_b32 s10, v151, 63
	s_nop 0
	v_mov_b32_e32 v151, s10
	v_fmamk_f32 v151, v151, 0x3a800000, v206
	v_cmp_gt_f32_e64 s[46:47], s8, v151
	v_mul_f32_e32 v153, 0x4b800000, v151
	s_nop 0
	v_cndmask_b32_e64 v151, v151, v153, s[46:47]
	v_rsq_f32_e32 v151, v151
	s_nop 0
	v_mul_f32_e32 v153, 0x45800000, v151
	v_cndmask_b32_e64 v176, v151, v153, s[46:47]
	v_pk_mul_f32 v[156:157], v[174:175], v[176:177] op_sel_hi:[1,0]
	v_pk_mul_f32 v[158:159], v[172:173], v[176:177] op_sel_hi:[1,0]
	v_and_b32_sdwa v172, v157, v205 dst_sel:DWORD dst_unused:UNUSED_PAD src0_sel:WORD_1 src1_sel:DWORD
	v_and_b32_sdwa v173, v159, v205 dst_sel:DWORD dst_unused:UNUSED_PAD src0_sel:WORD_1 src1_sel:DWORD
	v_and_b32_sdwa v151, v156, v205 dst_sel:DWORD dst_unused:UNUSED_PAD src0_sel:WORD_1 src1_sel:DWORD
	v_and_b32_sdwa v153, v158, v205 dst_sel:DWORD dst_unused:UNUSED_PAD src0_sel:WORD_1 src1_sel:DWORD
	v_add3_u32 v172, v157, v172, s91
	v_add3_u32 v173, v159, v173, s91
	v_add3_u32 v153, v158, v153, s91
	v_add3_u32 v151, v156, v151, s91
	v_and_b32_e32 v172, 0xffff0000, v172
	v_and_b32_e32 v174, 0xffff0000, v173
	v_or_b32_sdwa v173, v172, v151 dst_sel:DWORD dst_unused:UNUSED_PAD src0_sel:DWORD src1_sel:WORD_1
	v_or_b32_sdwa v172, v174, v153 dst_sel:DWORD dst_unused:UNUSED_PAD src0_sel:DWORD src1_sel:WORD_1
	v_lshl_add_u64 v[174:175], v[146:147], 0, v[178:179]
	v_pk_mul_f32 v[140:141], v[140:141], v[176:177] op_sel_hi:[1,0]
	v_pk_mul_f32 v[138:139], v[138:139], v[176:177] op_sel_hi:[1,0]
	global_store_dwordx2 v[174:175], v[172:173], off
	v_and_b32_sdwa v172, v141, v205 dst_sel:DWORD dst_unused:UNUSED_PAD src0_sel:WORD_1 src1_sel:DWORD
	v_and_b32_sdwa v173, v139, v205 dst_sel:DWORD dst_unused:UNUSED_PAD src0_sel:WORD_1 src1_sel:DWORD
	v_and_b32_sdwa v151, v140, v205 dst_sel:DWORD dst_unused:UNUSED_PAD src0_sel:WORD_1 src1_sel:DWORD
	v_and_b32_sdwa v153, v138, v205 dst_sel:DWORD dst_unused:UNUSED_PAD src0_sel:WORD_1 src1_sel:DWORD
	v_add3_u32 v172, v141, v172, s91
	v_add3_u32 v173, v139, v173, s91
	v_add3_u32 v153, v138, v153, s91
	v_add3_u32 v151, v140, v151, s91
	v_and_b32_e32 v172, 0xffff0000, v172
	v_and_b32_e32 v177, 0xffff0000, v173
	v_or_b32_sdwa v173, v172, v151 dst_sel:DWORD dst_unused:UNUSED_PAD src0_sel:DWORD src1_sel:WORD_1
	v_or_b32_sdwa v172, v177, v153 dst_sel:DWORD dst_unused:UNUSED_PAD src0_sel:DWORD src1_sel:WORD_1
	v_pk_mul_f32 v[136:137], v[136:137], v[176:177] op_sel_hi:[1,0]
	v_pk_mul_f32 v[134:135], v[134:135], v[176:177] op_sel_hi:[1,0]
	global_store_dwordx2 v[174:175], v[172:173], off offset:512
	v_and_b32_sdwa v172, v137, v205 dst_sel:DWORD dst_unused:UNUSED_PAD src0_sel:WORD_1 src1_sel:DWORD
	v_and_b32_sdwa v173, v135, v205 dst_sel:DWORD dst_unused:UNUSED_PAD src0_sel:WORD_1 src1_sel:DWORD
	v_and_b32_sdwa v151, v136, v205 dst_sel:DWORD dst_unused:UNUSED_PAD src0_sel:WORD_1 src1_sel:DWORD
	v_and_b32_sdwa v153, v134, v205 dst_sel:DWORD dst_unused:UNUSED_PAD src0_sel:WORD_1 src1_sel:DWORD
	v_add3_u32 v172, v137, v172, s91
	v_add3_u32 v173, v135, v173, s91
	v_add3_u32 v153, v134, v153, s91
	v_add3_u32 v151, v136, v151, s91
	v_and_b32_e32 v172, 0xffff0000, v172
	v_and_b32_e32 v177, 0xffff0000, v173
	v_or_b32_sdwa v173, v172, v151 dst_sel:DWORD dst_unused:UNUSED_PAD src0_sel:DWORD src1_sel:WORD_1
	v_or_b32_sdwa v172, v177, v153 dst_sel:DWORD dst_unused:UNUSED_PAD src0_sel:DWORD src1_sel:WORD_1
	v_pk_mul_f32 v[132:133], v[132:133], v[176:177] op_sel_hi:[1,0]
	v_pk_mul_f32 v[130:131], v[130:131], v[176:177] op_sel_hi:[1,0]
	global_store_dwordx2 v[174:175], v[172:173], off offset:1024
	v_and_b32_sdwa v172, v133, v205 dst_sel:DWORD dst_unused:UNUSED_PAD src0_sel:WORD_1 src1_sel:DWORD
	v_and_b32_sdwa v173, v131, v205 dst_sel:DWORD dst_unused:UNUSED_PAD src0_sel:WORD_1 src1_sel:DWORD
	v_and_b32_sdwa v151, v132, v205 dst_sel:DWORD dst_unused:UNUSED_PAD src0_sel:WORD_1 src1_sel:DWORD
	v_and_b32_sdwa v153, v130, v205 dst_sel:DWORD dst_unused:UNUSED_PAD src0_sel:WORD_1 src1_sel:DWORD
	v_add3_u32 v172, v133, v172, s91
	v_add3_u32 v173, v131, v173, s91
	v_add3_u32 v153, v130, v153, s91
	v_add3_u32 v151, v132, v151, s91
	v_and_b32_e32 v172, 0xffff0000, v172
	v_and_b32_e32 v176, 0xffff0000, v173
	v_or_b32_sdwa v173, v172, v151 dst_sel:DWORD dst_unused:UNUSED_PAD src0_sel:DWORD src1_sel:WORD_1
	v_or_b32_sdwa v172, v176, v153 dst_sel:DWORD dst_unused:UNUSED_PAD src0_sel:DWORD src1_sel:WORD_1
	global_store_dwordx2 v[174:175], v[172:173], off offset:1536
	v_pk_mul_f32 v[180:181], v[2:3], v[158:159]
	v_pk_mul_f32 v[182:183], v[18:19], v[158:159]
	v_pk_mul_f32 v[184:185], v[34:35], v[158:159]
	v_pk_mul_f32 v[186:187], v[50:51], v[158:159]
	v_pk_fma_f32 v[180:181], v[4:5], v[156:157], v[180:181]
	v_pk_fma_f32 v[182:183], v[20:21], v[156:157], v[182:183]
	v_pk_fma_f32 v[184:185], v[36:37], v[156:157], v[184:185]
	v_pk_fma_f32 v[186:187], v[52:53], v[156:157], v[186:187]
	v_pk_fma_f32 v[180:181], v[6:7], v[138:139], v[180:181]
	v_pk_fma_f32 v[182:183], v[22:23], v[138:139], v[182:183]
	v_pk_fma_f32 v[184:185], v[38:39], v[138:139], v[184:185]
	v_pk_fma_f32 v[186:187], v[54:55], v[138:139], v[186:187]
	v_pk_fma_f32 v[180:181], v[8:9], v[140:141], v[180:181]
	v_pk_fma_f32 v[182:183], v[24:25], v[140:141], v[182:183]
	v_pk_fma_f32 v[184:185], v[40:41], v[140:141], v[184:185]
	v_pk_fma_f32 v[186:187], v[56:57], v[140:141], v[186:187]
	v_pk_fma_f32 v[180:181], v[10:11], v[134:135], v[180:181]
	v_pk_fma_f32 v[182:183], v[26:27], v[134:135], v[182:183]
	v_pk_fma_f32 v[184:185], v[42:43], v[134:135], v[184:185]
	v_pk_fma_f32 v[186:187], v[58:59], v[134:135], v[186:187]
	v_pk_fma_f32 v[180:181], v[12:13], v[136:137], v[180:181]
	v_pk_fma_f32 v[182:183], v[28:29], v[136:137], v[182:183]
	v_pk_fma_f32 v[184:185], v[44:45], v[136:137], v[184:185]
	v_pk_fma_f32 v[186:187], v[60:61], v[136:137], v[186:187]
	v_pk_fma_f32 v[180:181], v[14:15], v[130:131], v[180:181]
	v_pk_fma_f32 v[182:183], v[30:31], v[130:131], v[182:183]
	v_pk_fma_f32 v[184:185], v[46:47], v[130:131], v[184:185]
	v_pk_fma_f32 v[186:187], v[62:63], v[130:131], v[186:187]
	v_pk_fma_f32 v[180:181], v[16:17], v[132:133], v[180:181]
	v_pk_fma_f32 v[182:183], v[32:33], v[132:133], v[182:183]
	v_pk_fma_f32 v[184:185], v[48:49], v[132:133], v[184:185]
	v_pk_fma_f32 v[186:187], v[64:65], v[132:133], v[186:187]
	v_add_f32_e32 v151, v180, v181
	v_add_f32_e32 v153, v182, v183
	v_add_f32_e32 v172, v184, v185
	v_add_f32_e32 v173, v186, v187
	v_pk_mul_f32 v[180:181], v[66:67], v[158:159]
	v_pk_mul_f32 v[182:183], v[82:83], v[158:159]
	v_pk_mul_f32 v[184:185], v[98:99], v[158:159]
	v_pk_mul_f32 v[186:187], v[114:115], v[158:159]
	v_pk_fma_f32 v[180:181], v[68:69], v[156:157], v[180:181]
	v_pk_fma_f32 v[182:183], v[84:85], v[156:157], v[182:183]
	v_pk_fma_f32 v[184:185], v[100:101], v[156:157], v[184:185]
	v_pk_fma_f32 v[186:187], v[116:117], v[156:157], v[186:187]
	v_pk_fma_f32 v[180:181], v[70:71], v[138:139], v[180:181]
	v_pk_fma_f32 v[182:183], v[86:87], v[138:139], v[182:183]
	v_pk_fma_f32 v[184:185], v[102:103], v[138:139], v[184:185]
	v_pk_fma_f32 v[186:187], v[118:119], v[138:139], v[186:187]
	v_pk_fma_f32 v[180:181], v[72:73], v[140:141], v[180:181]
	v_pk_fma_f32 v[182:183], v[88:89], v[140:141], v[182:183]
	v_pk_fma_f32 v[184:185], v[104:105], v[140:141], v[184:185]
	v_pk_fma_f32 v[186:187], v[120:121], v[140:141], v[186:187]
	v_pk_fma_f32 v[180:181], v[74:75], v[134:135], v[180:181]
	v_pk_fma_f32 v[182:183], v[90:91], v[134:135], v[182:183]
	v_pk_fma_f32 v[184:185], v[106:107], v[134:135], v[184:185]
	v_pk_fma_f32 v[186:187], v[122:123], v[134:135], v[186:187]
	v_pk_fma_f32 v[180:181], v[76:77], v[136:137], v[180:181]
	v_pk_fma_f32 v[182:183], v[92:93], v[136:137], v[182:183]
	v_pk_fma_f32 v[184:185], v[108:109], v[136:137], v[184:185]
	v_pk_fma_f32 v[186:187], v[124:125], v[136:137], v[186:187]
	v_pk_fma_f32 v[180:181], v[78:79], v[130:131], v[180:181]
	v_pk_fma_f32 v[182:183], v[94:95], v[130:131], v[182:183]
	v_pk_fma_f32 v[184:185], v[110:111], v[130:131], v[184:185]
	v_pk_fma_f32 v[186:187], v[126:127], v[130:131], v[186:187]
	v_pk_fma_f32 v[180:181], v[80:81], v[132:133], v[180:181]
	v_pk_fma_f32 v[182:183], v[96:97], v[132:133], v[182:183]
	v_pk_fma_f32 v[184:185], v[112:113], v[132:133], v[184:185]
	v_pk_fma_f32 v[186:187], v[128:129], v[132:133], v[186:187]
	v_add_f32_e32 v174, v180, v181
	v_add_f32_e32 v175, v182, v183
	v_add_f32_e32 v176, v184, v185
	v_add_f32_e32 v130, v186, v187
	v_cndmask_b32_e32 v131, v151, v174, vcc
	v_cndmask_b32_e32 v132, v153, v175, vcc
	v_cndmask_b32_e32 v133, v172, v176, vcc
	v_cndmask_b32_e32 v134, v173, v130, vcc
	ds_bpermute_b32 v131, v166, v131
	ds_bpermute_b32 v132, v166, v132
	ds_bpermute_b32 v133, v166, v133
	ds_bpermute_b32 v134, v166, v134
	v_cndmask_b32_e32 v180, v174, v151, vcc
	v_cndmask_b32_e32 v181, v175, v153, vcc
	v_cndmask_b32_e32 v182, v176, v172, vcc
	v_cndmask_b32_e32 v183, v130, v173, vcc
	s_waitcnt lgkmcnt(0)
	v_add_f32_e32 v131, v180, v131
	v_add_f32_e32 v132, v181, v132
	v_add_f32_e32 v133, v182, v133
	v_add_f32_e32 v130, v183, v134
	v_cndmask_b32_e64 v134, v131, v133, s[38:39]
	v_cndmask_b32_e64 v131, v133, v131, s[38:39]
	ds_bpermute_b32 v133, v167, v134
	s_waitcnt lgkmcnt(0)
	v_add_f32_e32 v131, v131, v133
	v_cndmask_b32_e64 v133, v132, v130, s[38:39]
	v_cndmask_b32_e64 v130, v130, v132, s[38:39]
	ds_bpermute_b32 v132, v167, v133
	s_waitcnt lgkmcnt(0)
	v_add_f32_e32 v130, v130, v132
	v_cndmask_b32_e64 v132, v131, v130, s[40:41]
	v_cndmask_b32_e64 v130, v130, v131, s[40:41]
	ds_bpermute_b32 v131, v168, v132
	s_waitcnt lgkmcnt(0)
	v_add_f32_e32 v130, v130, v131
	ds_bpermute_b32 v131, v169, v130
	s_waitcnt lgkmcnt(0)
	v_add_f32_e32 v130, v130, v131
	ds_bpermute_b32 v131, v170, v130
	s_waitcnt lgkmcnt(0)
	v_add_f32_e32 v130, v130, v131
	ds_bpermute_b32 v131, v171, v130
	s_waitcnt lgkmcnt(0)
	v_add_f32_e32 v130, v130, v131
	v_add_f32_e32 v130, v130, v241
	v_cmp_eq_u32_e64 s[46:47], s96, v244
	s_add_i32 s96, s96, 1
	v_cndmask_b32_e64 v242, v242, v130, s[46:47]
	v_cndmask_b32_e64 v243, v243, v142, s[46:47]
	s_cmp_lt_u32 s96, 8
	s_cbranch_scc1 .LBB0_641
.Lrmsf_flush:
	s_mov_b32 s96, 0
	v_mov_b32_e32 v130, v242
	v_cmp_le_i32_e64 s[46:47], 0, v243
	s_and_saveexec_b64 s[56:57], s[46:47]
	s_cbranch_execz .Lrmsf_fl_end
	v_cmp_ngt_f32_e64 s[46:47], 0, v130
	s_and_saveexec_b64 s[8:9], s[46:47]
	s_xor_b64 s[54:55], exec, s[8:9]
	s_cbranch_execz .LBB0_647
	v_mul_f32_e32 v131, 0xbfb8aa3b, v130
	v_rndne_f32_e32 v132, v131
	s_mov_b32 s8, 0xbfb8aa3b
	v_sub_f32_e32 v133, v131, v132
	v_fma_f32 v131, v130, s8, -v131
	v_fmac_f32_e32 v131, 0xb2a5705f, v130
	v_add_f32_e32 v131, v133, v131
	v_cvt_i32_f32_e32 v132, v132
	v_exp_f32_e32 v131, v131
	s_mov_b32 s8, 0x42ce8ed0
	v_cmp_nlt_f32_e64 s[46:47], s8, v130
	s_mov_b32 s8, 0xc2b17218
	v_ldexp_f32 v131, v131, v132
	v_cndmask_b32_e64 v131, 0, v131, s[46:47]
	v_cmp_ngt_f32_e64 s[46:47], s8, v130
	s_mov_b32 s8, 0x3f2aaaab
	s_nop 0
	v_cndmask_b32_e64 v151, v220, v131, s[46:47]
	v_add_f32_e32 v132, 1.0, v151
	v_add_f32_e32 v130, -1.0, v132
	v_sub_f32_e32 v131, v130, v132
	v_add_f32_e32 v131, 1.0, v131
	v_sub_f32_e32 v130, v151, v130
	v_add_f32_e32 v133, v130, v131
	v_frexp_mant_f32_e32 v134, v132
	v_cvt_f64_f32_e32 v[130:131], v132
	v_frexp_exp_i32_f64_e32 v130, v[130:131]
	v_cmp_gt_f32_e64 s[46:47], s8, v134
	s_mov_b32 s8, 0x3f317218
	s_nop 0
	v_subbrev_co_u32_e64 v138, s[46:47], 0, v130, s[46:47]
	v_sub_u32_e32 v130, 0, v138
	v_ldexp_f32 v131, v132, v130
	v_add_f32_e32 v132, -1.0, v131
	v_add_f32_e32 v134, 1.0, v131
	v_ldexp_f32 v130, v133, v130
	v_add_f32_e32 v133, 1.0, v132
	v_add_f32_e32 v135, -1.0, v134
	v_sub_f32_e32 v133, v131, v133
	v_sub_f32_e32 v131, v131, v135
	v_add_f32_e32 v133, v130, v133
	v_add_f32_e32 v130, v130, v131
	v_add_f32_e32 v139, v134, v130
	v_rcp_f32_e32 v141, v139
	v_sub_f32_e32 v131, v134, v139
	v_add_f32_e32 v140, v130, v131
	v_add_f32_e32 v131, v132, v133
	v_mul_f32_e32 v156, v131, v141
	v_sub_f32_e32 v130, v132, v131
	v_mul_f32_e32 v132, v139, v156
	v_fma_f32 v134, v156, v139, -v132
	v_fmac_f32_e32 v134, v156, v140
	v_add_f32_e32 v153, v133, v130
	v_add_f32_e32 v130, v132, v134
	v_sub_f32_e32 v133, v131, v130
	v_pk_add_f32 v[136:137], v[130:131], v[132:133] neg_lo:[0,1] neg_hi:[0,1]
	v_mov_b32_e32 v135, v130
	v_pk_add_f32 v[130:131], v[136:137], v[134:135] neg_lo:[0,1] neg_hi:[0,1]
	s_nop 0
	v_add_f32_e32 v131, v153, v131
	v_add_f32_e32 v130, v130, v131
	v_add_f32_e32 v131, v133, v130
	v_mul_f32_e32 v153, v141, v131
	v_mul_f32_e32 v132, v139, v153
	v_fma_f32 v134, v153, v139, -v132
	v_fmac_f32_e32 v134, v153, v140
	v_sub_f32_e32 v133, v133, v131
	v_add_f32_e32 v139, v130, v133
	v_add_f32_e32 v130, v132, v134
	v_sub_f32_e32 v133, v131, v130
	v_pk_add_f32 v[136:137], v[130:131], v[132:133] neg_lo:[0,1] neg_hi:[0,1]
	v_mov_b32_e32 v135, v130
	v_pk_add_f32 v[130:131], v[136:137], v[134:135] neg_lo:[0,1] neg_hi:[0,1]
	s_nop 0
	v_add_f32_e32 v131, v139, v131
	v_add_f32_e32 v130, v130, v131
	v_add_f32_e32 v131, v156, v153
	v_add_f32_e32 v130, v133, v130
	v_sub_f32_e32 v132, v131, v156
	v_mul_f32_e32 v130, v141, v130
	v_sub_f32_e32 v132, v153, v132
	v_add_f32_e32 v132, v132, v130
	v_add_f32_e32 v134, v131, v132
	v_mul_f32_e32 v135, v134, v134
	v_fmamk_f32 v130, v135, 0x3e9b6dac, v207
	v_fmaak_f32 v197, v135, v130, 0x3f2aaada
	v_cvt_f32_i32_e32 v130, v138
	v_sub_f32_e32 v131, v134, v131
	v_sub_f32_e32 v131, v132, v131
	v_ldexp_f32 v136, v131, 1
	v_mul_f32_e32 v131, v134, v135
	v_ldexp_f32 v133, v134, 1
	v_pk_mul_f32 v[134:135], v[130:131], v[196:197]
	s_nop 0
	v_fma_f32 v132, v130, s8, -v134
	v_fmac_f32_e32 v132, 0xb102e308, v130
	v_pk_add_f32 v[130:131], v[134:135], v[132:133]
	s_mov_b32 s8, 0x7f800000
	v_sub_f32_e32 v133, v131, v133
	v_sub_f32_e32 v133, v135, v133
	v_add_f32_e32 v137, v136, v133
	v_mov_b32_e32 v136, v134
	v_pk_add_f32 v[134:135], v[130:131], v[134:135] neg_lo:[0,1] neg_hi:[0,1]
	v_pk_add_f32 v[138:139], v[130:131], v[136:137]
	v_mov_b32_e32 v133, v130
	v_mov_b32_e32 v135, v139
	v_pk_add_f32 v[140:141], v[132:133], v[134:135] neg_lo:[0,1] neg_hi:[0,1]
	v_pk_add_f32 v[132:133], v[132:133], v[134:135]
	v_mov_b32_e32 v136, v137
	v_pk_add_f32 v[134:135], v[132:133], v[130:131] op_sel:[1,0] op_sel_hi:[0,1] neg_lo:[0,1] neg_hi:[0,1]
	v_pk_add_f32 v[156:157], v[138:139], v[134:135] op_sel_hi:[1,0] neg_lo:[0,1] neg_hi:[0,1]
	v_mov_b32_e32 v138, v139
	v_mov_b32_e32 v139, v133
	v_pk_mov_b32 v[134:135], v[130:131], v[134:135] op_sel:[1,0]
	v_mov_b32_e32 v137, v130
	v_pk_add_f32 v[134:135], v[138:139], v[134:135] neg_lo:[0,1] neg_hi:[0,1]
	v_mov_b32_e32 v156, v140
	v_pk_add_f32 v[130:131], v[136:137], v[134:135] neg_lo:[0,1] neg_hi:[0,1]
	v_mov_b32_e32 v141, v133
	v_pk_add_f32 v[134:135], v[156:157], v[130:131]
	v_cmp_neq_f32_e64 s[46:47], s8, v151
	v_pk_add_f32 v[136:137], v[134:135], v[134:135] op_sel:[0,1] op_sel_hi:[1,0]
	s_mov_b32 s8, 0x33800000
	v_pk_add_f32 v[132:133], v[132:133], v[136:137] op_sel:[1,0] op_sel_hi:[0,1]
	v_mov_b32_e32 v135, v132
	v_pk_add_f32 v[138:139], v[134:135], v[140:141] neg_lo:[0,1] neg_hi:[0,1]
	v_mov_b32_e32 v131, v136
	v_sub_f32_e32 v133, v134, v138
	v_pk_add_f32 v[130:131], v[130:131], v[138:139] neg_lo:[0,1] neg_hi:[0,1]
	v_sub_f32_e32 v133, v140, v133
	v_add_f32_e32 v130, v130, v133
	v_add_f32_e32 v130, v130, v131
	v_add_f32_e32 v130, v132, v130
	v_cndmask_b32_e64 v130, v220, v130, s[46:47]
	v_cmp_lt_f32_e64 s[46:47], |v151|, s8
	s_nop 1
	v_cndmask_b32_e64 v130, v130, v151, s[46:47]
	v_xor_b32_e32 v131, 0x80000000, v130

.LBB0_649:
	s_or_b64 exec, exec, s[24:25]
	s_cmp_eq_u32 s96, 0
	s_cbranch_scc1 .Lrmsf_done
	s_mov_b32 s97, 1
	s_branch .Lrmsf_flush
.Lrmsf_done:
.LBB0_650:
	v_readlane_b32 s4, v255, 3
	s_add_i32 s4, s4, 3
	s_cmp_lt_i32 s4, s85
	s_cselect_b64 s[24:25], -1, 0
	s_and_b64 s[0:1], s[0:1], s[24:25]
	s_andn2_b64 vcc, exec, s[0:1]
	s_cbranch_vccnz .LBB0_721
	s_waitcnt vmcnt(0)
	s_waitcnt vmcnt(0) lgkmcnt(0)
	s_barrier
	s_mov_b64 s[0:1], exec
	v_readlane_b32 s8, v253, 0
	v_readlane_b32 s9, v253, 1
	s_and_b64 s[8:9], s[0:1], s[8:9]
	s_mov_b64 exec, s[8:9]
	s_cbranch_execz .LBB0_720
	v_readlane_b32 s5, v254, 57
	s_waitcnt vmcnt(0) expcnt(0) lgkmcnt(0)
	s_nop 0
	v_mov_b32_e32 v0, s5
	ds_read_b32 v3, v0
	v_readlane_b32 s5, v254, 58
	s_waitcnt lgkmcnt(0)
	v_cmp_ne_u32_e32 vcc, 0, v3
	v_mov_b32_e32 v0, s5
	ds_read_b32 v2, v0
	s_cbranch_vccnz .LBB0_667
	s_mov_b32 s5, 1
	s_branch .LBB0_655
